# window branch: K tile copies removed, QK MFMAs read the prefetch registers and the next K tile is loaded right after them
# baseline (speedup 1.0000x reference)
; __device__ __forceinline__ void nsa_unit(const Params& p, int bg, int jq, LAS unsigned char* lds, int wave, int lane, bool build_lut) {
;     ...
;         for (int T = T0; T <= T1; ++T) {
; #pragma unroll
;             for (int ks = 0; ks < 4; ++ks) kf[ks] = kn[ks];
;             load_v(vf, vwT + (size_t)T * 2048, lane);
;             if (T < T1) load_k(kn, kwb + (size_t)(32 * (T + 1)) * 64, lane);
;             const int base = 32 * T;
;             f32x16 s = qk_tile(kf, qf);
;             if (((tq0 - base - 31) >= 128) && ((tq0 + 7 - base) < 512)) online_step<true>(s, lutfar, true, m, l, o0, o1, vf);
.LBB0_1284:
	s_waitcnt lgkmcnt(0)
	v_mfma_f32_32x32x16_bf16 v[48:63], v[2:5], v[140:143], 0
	s_add_i32 s5, s13, -7
	s_cmpk_gt_i32 s5, 0x9e
	s_cselect_b64 s[10:11], -1, 0
	s_cmpk_lt_i32 s13, 0x200
	s_cselect_b64 s[16:17], -1, 0
	s_and_b64 s[16:17], s[10:11], s[16:17]
	s_mov_b64 s[10:11], -1
	v_mfma_f32_32x32x16_bf16 v[48:63], v[6:9], v[136:139], v[48:63]
	s_andn2_b64 vcc, exec, s[16:17]
	v_mfma_f32_32x32x16_bf16 v[48:63], v[10:13], v[132:135], v[48:63]
	v_mfma_f32_32x32x16_bf16 v[48:63], v[144:147], v[128:131], v[48:63]
	s_cmp_ge_i32 s4, s12
	s_cbranch_scc1 .Lw_noload
	s_ashr_i32 s7, s6, 31
	s_lshl_b64 s[100:101], s[6:7], 7
	v_lshl_add_u64 v[238:239], v[14:15], 0, s[100:101]
	global_load_dwordx4 v[2:5], v[238:239], off
	global_load_dwordx4 v[6:9], v[238:239], off offset:1024
	global_load_dwordx4 v[10:13], v[238:239], off offset:2048
	global_load_dwordx4 v[144:147], v[238:239], off offset:3072
; #define LAS __attribute__((address_space(3)))
; __device__ __forceinline__ float fast_exp2(float x) { return __builtin_amdgcn_exp2f(x); }
; __device__ __forceinline__ float xhalf_max(float x) { auto t = __builtin_amdgcn_permlane32_swap(__float_as_uint(x), __float_as_uint(x), false, false); return fmaxf(__uint_as_float(t[0]), __uint_as_float(t[1])); }
; template <int STRIDE> __device__ __forceinline__ void score_tile(f32x16& s, int dl, int dmax, bool lane_ok, bool fast, float lutfar, const LAS float* lutr) {
;     if (fast) {
; #pragma unroll
;         for (int i = 0; i < 16; ++i) s[i] = lane_ok ? (s[i] + lutfar) : NEG_INF;
;     } else {
; #pragma unroll
;         for (int i = 0; i < 16; ++i) {
;             const int d = dl - STRIDE * ((i & 3) + 8 * (i >> 2));
;             const bool ok = lane_ok && d >= 0 && d < dmax;
;             const int di = min(max(d, 0), 128);
;             s[i] = ok ? (s[i] + lutr[di]) : NEG_INF;
;         }
;     }
; }
; template <bool FAST> __device__ __forceinline__ void online_step(f32x16& s, float bias, bool lane_ok, float& m, float& l, f32x16& o0, f32x16& o1, const bf16x8 (&vf)[2][2]) {
;     float mx = fmaxf(fmaxf(fmaxf(s[0], s[1]), fmaxf(s[2], s[3])), fmaxf(fmaxf(s[4], s[5]), fmaxf(s[6], s[7])));
;     mx = fmaxf(mx, fmaxf(fmaxf(fmaxf(s[8], s[9]), fmaxf(s[10], s[11])), fmaxf(fmaxf(s[12], s[13]), fmaxf(s[14], s[15]))));
;     if (FAST) { mx += bias; mx = lane_ok ? mx : NEG_INF; }
;     mx = xhalf_max(mx);
;     if (__any(mx > m + 8.0f)) {
;         const float mnew = (mx > m + 8.0f) ? mx : m;
;         const float alpha = fast_exp2(m - mnew);
;         l *= alpha; m = mnew;
; #pragma unroll
;         for (int i = 0; i < 16; ++i) { o0[i] *= alpha; o1[i] *= alpha; }
.Lw_noload:
	s_cbranch_vccz .LBB0_1320
	v_add_u32_e32 v64, s13, v180
	v_mov_b32_e32 v240, 0xff800000
	v_add_u32_e32 v164, -7, v64
	v_min_u32_e32 v164, 0x80, v164
	v_lshl_add_u32 v164, v164, 2, v231
	ds_read_b32 v164, v164 offset:8448
	v_add_u32_e32 v1, -8, v64
	v_min_u32_e32 v1, 0x80, v1
	v_lshl_add_u32 v1, v1, 2, v231
	ds_read_b32 v1, v1 offset:8448
	v_add_u32_e32 v166, -9, v64
	v_min_u32_e32 v166, 0x80, v166
	v_lshl_add_u32 v166, v166, 2, v231
	ds_read_b32 v166, v166 offset:8448
	v_add_u32_e32 v165, -10, v64
	v_min_u32_e32 v165, 0x80, v165
	v_lshl_add_u32 v165, v165, 2, v231
	ds_read_b32 v165, v165 offset:8448
	v_add_u32_e32 v168, -15, v64
	v_min_u32_e32 v168, 0x80, v168
	v_lshl_add_u32 v168, v168, 2, v231
	ds_read_b32 v168, v168 offset:8448
	v_add_u32_e32 v167, -16, v64
	v_min_u32_e32 v167, 0x80, v167
	v_lshl_add_u32 v167, v167, 2, v231
	ds_read_b32 v167, v167 offset:8448
	v_subrev_u32_e32 v170, 17, v64
	v_min_u32_e32 v170, 0x80, v170
	v_lshl_add_u32 v170, v170, 2, v231
	ds_read_b32 v170, v170 offset:8448
	v_subrev_u32_e32 v169, 18, v64
	v_min_u32_e32 v169, 0x80, v169
	v_lshl_add_u32 v169, v169, 2, v231
	ds_read_b32 v169, v169 offset:8448
	v_subrev_u32_e32 v172, 23, v64
	v_min_u32_e32 v172, 0x80, v172
	v_lshl_add_u32 v172, v172, 2, v231
	ds_read_b32 v172, v172 offset:8448
	v_subrev_u32_e32 v171, 24, v64
	v_min_u32_e32 v171, 0x80, v171
	v_lshl_add_u32 v171, v171, 2, v231
	ds_read_b32 v171, v171 offset:8448
	v_subrev_u32_e32 v174, 25, v64
	v_min_u32_e32 v174, 0x80, v174
	v_lshl_add_u32 v174, v174, 2, v231
	ds_read_b32 v174, v174 offset:8448
	v_subrev_u32_e32 v173, 26, v64
	v_min_u32_e32 v173, 0x80, v173
	v_lshl_add_u32 v173, v173, 2, v231
	ds_read_b32 v173, v173 offset:8448
	v_subrev_u32_e32 v234, 31, v64
	v_min_u32_e32 v234, 0x80, v234
	v_lshl_add_u32 v234, v234, 2, v231
	ds_read_b32 v234, v234 offset:8448
	v_subrev_u32_e32 v175, 32, v64
	v_min_u32_e32 v175, 0x80, v175
	v_lshl_add_u32 v175, v175, 2, v231
	ds_read_b32 v175, v175 offset:8448
	v_subrev_u32_e32 v235, 33, v64
	v_min_u32_e32 v235, 0x80, v235
	v_lshl_add_u32 v235, v235, 2, v231
	ds_read_b32 v235, v235 offset:8448
	v_subrev_u32_e32 v232, 34, v64
	v_min_u32_e32 v232, 0x80, v232
	v_lshl_add_u32 v232, v232, 2, v231
	ds_read_b32 v232, v232 offset:8448
	v_add_u32_e32 v238, -7, v64
	s_waitcnt lgkmcnt(15)
	v_cmp_gt_u32_e32 vcc, s77, v238
	v_add_u32_e32 v239, -8, v64
	v_add_f32_e32 v164, v48, v164
	v_cndmask_b32_e32 v164, v240, v164, vcc
	v_cmp_gt_u32_e32 vcc, s77, v239
	v_add_u32_e32 v238, -9, v64
	s_waitcnt lgkmcnt(14)
	v_add_f32_e32 v1, v49, v1
	v_cndmask_b32_e32 v1, v240, v1, vcc
	v_cmp_gt_u32_e32 vcc, s77, v238
	v_add_u32_e32 v239, -10, v64
	s_waitcnt lgkmcnt(13)
	v_add_f32_e32 v166, v50, v166
	v_cndmask_b32_e32 v166, v240, v166, vcc
	v_cmp_gt_u32_e32 vcc, s77, v239
	v_add_u32_e32 v238, -15, v64
	s_waitcnt lgkmcnt(12)
	v_add_f32_e32 v165, v51, v165
	v_cndmask_b32_e32 v165, v240, v165, vcc
	v_cmp_gt_u32_e32 vcc, s77, v238
	v_add_u32_e32 v239, -16, v64
	s_waitcnt lgkmcnt(11)
	v_add_f32_e32 v168, v52, v168
	v_cndmask_b32_e32 v168, v240, v168, vcc
	v_cmp_gt_u32_e32 vcc, s77, v239
	v_subrev_u32_e32 v238, 17, v64
	s_waitcnt lgkmcnt(10)
	v_add_f32_e32 v167, v53, v167
	v_cndmask_b32_e32 v167, v240, v167, vcc
	v_cmp_gt_u32_e32 vcc, s77, v238
	v_subrev_u32_e32 v239, 18, v64
	s_waitcnt lgkmcnt(9)
	v_add_f32_e32 v170, v54, v170
	v_cndmask_b32_e32 v170, v240, v170, vcc
	v_cmp_gt_u32_e32 vcc, s77, v239
	v_subrev_u32_e32 v238, 23, v64
	s_waitcnt lgkmcnt(8)
	v_add_f32_e32 v169, v55, v169
	v_cndmask_b32_e32 v169, v240, v169, vcc
	v_cmp_gt_u32_e32 vcc, s77, v238
	v_subrev_u32_e32 v239, 24, v64
	s_waitcnt lgkmcnt(7)
	v_add_f32_e32 v172, v56, v172
	v_cndmask_b32_e32 v172, v240, v172, vcc
	v_cmp_gt_u32_e32 vcc, s77, v239
	v_subrev_u32_e32 v238, 25, v64
	s_waitcnt lgkmcnt(6)
	v_add_f32_e32 v171, v57, v171
	v_cndmask_b32_e32 v171, v240, v171, vcc
	v_cmp_gt_u32_e32 vcc, s77, v238
	v_subrev_u32_e32 v239, 26, v64
	s_waitcnt lgkmcnt(5)
	v_add_f32_e32 v174, v58, v174
	v_cndmask_b32_e32 v174, v240, v174, vcc
	v_cmp_gt_u32_e32 vcc, s77, v239
	v_subrev_u32_e32 v238, 31, v64
	s_waitcnt lgkmcnt(4)
	v_add_f32_e32 v173, v59, v173
	v_cndmask_b32_e32 v173, v240, v173, vcc
	v_cmp_gt_u32_e32 vcc, s77, v238
	v_subrev_u32_e32 v239, 32, v64
	s_waitcnt lgkmcnt(3)
	v_add_f32_e32 v234, v60, v234
	v_cndmask_b32_e32 v234, v240, v234, vcc
	v_cmp_gt_u32_e32 vcc, s77, v239
	v_subrev_u32_e32 v238, 33, v64
	s_waitcnt lgkmcnt(2)
	v_add_f32_e32 v175, v61, v175
	v_cndmask_b32_e32 v175, v240, v175, vcc
	v_cmp_gt_u32_e32 vcc, s77, v238
	v_subrev_u32_e32 v239, 34, v64
	s_waitcnt lgkmcnt(1)
	v_add_f32_e32 v235, v62, v235
	v_cndmask_b32_e32 v235, v240, v235, vcc
	v_cmp_gt_u32_e32 vcc, s77, v239
	s_nop 0
	s_waitcnt lgkmcnt(0)
	v_add_f32_e32 v232, v63, v232
	v_cndmask_b32_e32 v232, v240, v232, vcc
	v_max3_f32 v64, v164, v1, v166
	v_max3_f32 v65, v165, v168, v167
	v_max3_f32 v66, v170, v169, v172
	v_max3_f32 v67, v171, v174, v173
	v_max3_f32 v68, v234, v175, v235
	v_max3_f32 v64, v64, v65, v232
	v_max3_f32 v64, v64, v66, v67
	v_max_f32_e32 v64, v64, v68
	v_mov_b32_e32 v65, v64
	s_nop 1
	v_permlane32_swap_b32_e32 v64, v65
	v_max_f32_e32 v237, v64, v65
	v_add_f32_e32 v64, 0x41000000, v185
	v_cmp_gt_f32_e32 vcc, v237, v64
	v_mov_b32_e32 v233, v185
	v_mov_b32_e32 v236, v189
	s_cbranch_vccz .LBB0_1319
	v_cndmask_b32_e32 v233, v185, v237, vcc
	v_sub_f32_e32 v64, v185, v233
	v_exp_f32_e32 v80, v64
	s_nop 0
	v_mul_f32_e32 v236, v189, v80
	v_pk_mul_f32 v[30:31], v[30:31], v[80:81] op_sel_hi:[1,0]
	v_pk_mul_f32 v[28:29], v[28:29], v[80:81] op_sel_hi:[1,0]
	v_pk_mul_f32 v[26:27], v[26:27], v[80:81] op_sel_hi:[1,0]
	v_pk_mul_f32 v[24:25], v[24:25], v[80:81] op_sel_hi:[1,0]
	v_pk_mul_f32 v[22:23], v[22:23], v[80:81] op_sel_hi:[1,0]
	v_pk_mul_f32 v[20:21], v[20:21], v[80:81] op_sel_hi:[1,0]
	v_pk_mul_f32 v[18:19], v[18:19], v[80:81] op_sel_hi:[1,0]
	v_pk_mul_f32 v[16:17], v[16:17], v[80:81] op_sel_hi:[1,0]
	v_pk_mul_f32 v[46:47], v[46:47], v[80:81] op_sel_hi:[1,0]
	v_pk_mul_f32 v[44:45], v[44:45], v[80:81] op_sel_hi:[1,0]
	v_pk_mul_f32 v[42:43], v[42:43], v[80:81] op_sel_hi:[1,0]
	v_pk_mul_f32 v[40:41], v[40:41], v[80:81] op_sel_hi:[1,0]
	v_pk_mul_f32 v[38:39], v[38:39], v[80:81] op_sel_hi:[1,0]
	v_pk_mul_f32 v[36:37], v[36:37], v[80:81] op_sel_hi:[1,0]
	v_pk_mul_f32 v[34:35], v[34:35], v[80:81] op_sel_hi:[1,0]
	v_pk_mul_f32 v[32:33], v[32:33], v[80:81] op_sel_hi:[1,0]

; __device__ __forceinline__ void nsa_unit(const Params& p, int bg, int jq, LAS unsigned char* lds, int wave, int lane, bool build_lut) {
;     ...
;         load_k(kn, kwb + (size_t)(32 * T0) * 64, lane);
;         for (int T = T0; T <= T1; ++T) {
; #pragma unroll
;             for (int ks = 0; ks < 4; ++ks) kf[ks] = kn[ks];
;             load_v(vf, vwT + (size_t)T * 2048, lane);
;             if (T < T1) load_k(kn, kwb + (size_t)(32 * (T + 1)) * 64, lane);
;             const int base = 32 * T;
;             f32x16 s = qk_tile(kf, qf);
;             if (((tq0 - base - 31) >= 128) && ((tq0 + 7 - base) < 512)) online_step<true>(s, lutfar, true, m, l, o0, o1, vf);
;             else { score_tile<1>(s, tq - base - 4 * h, 512, true, false, lutfar, lutr); online_step<false>(s, 0.f, true, m, l, o0, o1, vf); }
;         }
.LBB0_1324:
	s_add_i32 s4, s4, 1
	s_sub_i32 s13, s13, 32
	s_add_i32 s6, s6, 32
	s_andn2_b64 vcc, exec, s[8:9]
	v_lshl_add_u64 v[220:221], v[220:221], 0, s[84:85]
	s_cbranch_vccz .LBB0_1326
	s_waitcnt vmcnt(0)
	v_mov_b32_e32 v189, v232
	v_mov_b32_e32 v185, v233
	s_branch .LBB0_1282
